# speedup vs baseline: 1.0022x; 1.0022x over previous
; __device__ __forceinline__ int crow(int r, int hi) { return (r & 3) + 8 * (r >> 2) + 4 * hi; }
; __device__ __forceinline__ void attn_body3(const bf16* __restrict__ Qb, const bf16* __restrict__ Kh, const bf16* __restrict__ Vh,
;                                            bf16* __restrict__ Ob, int seq, int qpos0, float slS, float mraw, char* lds, const int tid) {
;     ...
;   { auto rr = __builtin_amdgcn_permlane32_swap(__float_as_uint(lsum), __float_as_uint(lsum), false, false);
;     lsum = __uint_as_float(rr[0]) + __uint_as_float(rr[1]); }
;   __syncthreads();
;   float* li = (float*)(lds + A3_X) + pair * 64;
;   if (hi == 0) li[role * 32 + r32] = lsum;
;   __syncthreads();
;   float rli[16];
; #pragma unroll
;   for (int r = 0; r < 16; ++r) { const int rw = crow(r, hi); rli[r] = __builtin_amdgcn_rcpf(li[rw] + li[32 + rw]); }
;   __syncthreads();
.LBB0_146:
	s_or_b64 exec, exec, s[0:1]
	v_lshl_add_u32 v0, v164, 2, s2
	s_waitcnt lgkmcnt(0)
	s_barrier
	ds_read_b128 v[4:7], v0
	ds_read_b128 v[8:11], v0 offset:32
	ds_read_b128 v[12:15], v0 offset:128
	s_lshl_b32 s0, s63, 26
	s_add_u32 s3, s14, s0
	s_addc_u32 s8, s15, 0
	s_lshl_b64 s[0:1], s[70:71], 12
	s_waitcnt lgkmcnt(0)
	v_add_f32_e32 v1, v4, v12
	v_add_f32_e32 v4, v6, v14
	v_rcp_f32_e32 v12, v4
	v_add_f32_e32 v4, v7, v15
	v_add_f32_e32 v2, v5, v13
	v_rcp_f32_e32 v13, v4
	ds_read_b128 v[4:7], v0 offset:160
	s_add_u32 s0, s3, s0
	s_addc_u32 s1, s8, s1
	v_rcp_f32_e32 v1, v1
	s_add_u32 s0, s0, s72
	s_waitcnt lgkmcnt(0)
	v_add_f32_e32 v4, v8, v4
	v_rcp_f32_e32 v14, v4
	v_add_f32_e32 v4, v9, v5
	v_rcp_f32_e32 v15, v4
	v_add_f32_e32 v4, v10, v6
	v_rcp_f32_e32 v80, v4
	v_add_f32_e32 v4, v11, v7
	v_rcp_f32_e32 v81, v4
	ds_read_b128 v[4:7], v0 offset:64
	ds_read_b128 v[8:11], v0 offset:192
	s_addc_u32 s1, s1, s73
	v_rcp_f32_e32 v2, v2
	s_lshl_b32 s2, s79, 14
	s_add_i32 s2, s2, 0
	s_waitcnt lgkmcnt(0)
	v_add_f32_e32 v4, v4, v8
	v_rcp_f32_e32 v82, v4
	v_add_f32_e32 v4, v5, v9
	v_rcp_f32_e32 v83, v4
	v_add_f32_e32 v4, v6, v10
	v_rcp_f32_e32 v84, v4
	v_add_f32_e32 v4, v7, v11
	v_rcp_f32_e32 v85, v4
	ds_read_b128 v[4:7], v0 offset:96
	ds_read_b128 v[8:11], v0 offset:224
	s_waitcnt lgkmcnt(0)
	s_barrier
; __device__ __forceinline__ void attn_body3(const bf16* __restrict__ Qb, const bf16* __restrict__ Kh, const bf16* __restrict__ Vh,
;                                            bf16* __restrict__ Ob, int seq, int qpos0, float slS, float mraw, char* lds, const int tid) {
;     ...
;   { float* ol = (float*)lds + wid * 4096;
;     int lw = (4 * hi) * 128 + r32; asm volatile("" : "+v"(lw));
; #pragma unroll
;     for (int r = 0; r < 16; ++r) { const int orow = (r & 3) + 8 * (r >> 2);
; #pragma unroll
;       for (int d0 = 0; d0 < 4; ++d0) ol[lw + orow * 128 + d0 * 32] = o[d0][r] * rli[r]; }
;     asm volatile("s_waitcnt lgkmcnt(0)" ::: "memory");
;     int lr = (lane >> 5) * 128 + (lane & 31) * 4; asm volatile("" : "+v"(lr));
;     bf16* Ow = Ob + (pair * QBLK + (lane >> 5)) * LDO + role * 128 + (lane & 31) * 4;
; #pragma unroll
;     for (int i2 = 0; i2 < 16; ++i2) { const f32x4 v = *reinterpret_cast<const f32x4*>(ol + lr + i2 * 256);
;       u32x2 w = {cvtpk(v[0], v[1]), cvtpk(v[2], v[3])};
;       *reinterpret_cast<u32x2*>(Ow + i2 * 2 * LDO) = w; } }
	v_mov_b32_e32 v147, v3
	v_add_f32_e32 v0, v4, v8
	v_add_f32_e32 v4, v5, v9
	v_add_f32_e32 v5, v6, v10
	v_add_f32_e32 v6, v7, v11
	v_mov_b32_e32 v7, v177
	v_mul_f32_e32 v8, v32, v1
	v_lshl_add_u32 v7, v7, 2, s2
	v_mul_f32_e32 v9, v16, v1
	ds_write2_b32 v7, v8, v9 offset1:32
	v_mul_f32_e32 v8, v64, v1
	v_mul_f32_e32 v1, v48, v1
	ds_write2_b32 v7, v8, v1 offset0:64 offset1:96
	v_mul_f32_e32 v1, v33, v2
	v_mul_f32_e32 v8, v17, v2
	ds_write2_b32 v7, v1, v8 offset0:128 offset1:160
	v_mul_f32_e32 v1, v65, v2
	v_mul_f32_e32 v2, v49, v2
	ds_write2_b32 v7, v1, v2 offset0:192 offset1:224
	v_mul_f32_e32 v1, v34, v12
	v_mul_f32_e32 v2, v18, v12
	v_add_u32_e32 v8, 0x400, v7
	ds_write2_b32 v8, v1, v2 offset1:32
	v_mul_f32_e32 v1, v66, v12
	v_mul_f32_e32 v2, v50, v12
	ds_write2_b32 v8, v1, v2 offset0:64 offset1:96
	v_mul_f32_e32 v1, v35, v13
	v_mul_f32_e32 v2, v19, v13
	ds_write2_b32 v8, v1, v2 offset0:128 offset1:160
	v_mul_f32_e32 v1, v67, v13
	v_mul_f32_e32 v2, v51, v13
	ds_write2_b32 v8, v1, v2 offset0:192 offset1:224
	v_mul_f32_e32 v1, v36, v14
	v_mul_f32_e32 v2, v20, v14
	v_add_u32_e32 v8, 0x1000, v7
	ds_write2_b32 v8, v1, v2 offset1:32
	v_mul_f32_e32 v1, v68, v14
	v_mul_f32_e32 v2, v52, v14
	ds_write2_b32 v8, v1, v2 offset0:64 offset1:96
	v_mul_f32_e32 v1, v37, v15
	v_mul_f32_e32 v2, v21, v15
	ds_write2_b32 v8, v1, v2 offset0:128 offset1:160
	v_mul_f32_e32 v1, v69, v15
	v_mul_f32_e32 v2, v53, v15
	ds_write2_b32 v8, v1, v2 offset0:192 offset1:224
	v_mul_f32_e32 v1, v38, v80
	v_mul_f32_e32 v2, v22, v80
	v_add_u32_e32 v8, 0x1400, v7
	ds_write2_b32 v8, v1, v2 offset1:32
	v_mul_f32_e32 v1, v70, v80
	v_mul_f32_e32 v2, v54, v80
	ds_write2_b32 v8, v1, v2 offset0:64 offset1:96
	v_mul_f32_e32 v1, v39, v81
	v_mul_f32_e32 v2, v23, v81
	ds_write2_b32 v8, v1, v2 offset0:128 offset1:160
	v_mul_f32_e32 v1, v71, v81
	v_mul_f32_e32 v2, v55, v81
	ds_write2_b32 v8, v1, v2 offset0:192 offset1:224
	v_mul_f32_e32 v1, v40, v82
	v_mul_f32_e32 v2, v24, v82
	v_add_u32_e32 v8, 0x2000, v7
	ds_write2_b32 v8, v1, v2 offset1:32
	v_mul_f32_e32 v1, v72, v82
	v_mul_f32_e32 v2, v56, v82
	ds_write2_b32 v8, v1, v2 offset0:64 offset1:96
	v_mul_f32_e32 v1, v41, v83
	v_mul_f32_e32 v2, v25, v83
	ds_write2_b32 v8, v1, v2 offset0:128 offset1:160
	v_mul_f32_e32 v1, v73, v83
	v_mul_f32_e32 v2, v57, v83
	v_rcp_f32_e32 v0, v0
	ds_write2_b32 v8, v1, v2 offset0:192 offset1:224
	v_mul_f32_e32 v1, v42, v84
	v_mul_f32_e32 v2, v26, v84
	v_add_u32_e32 v8, 0x2400, v7
	ds_write2_b32 v8, v1, v2 offset1:32
	v_mul_f32_e32 v1, v74, v84
	v_mul_f32_e32 v2, v58, v84
	v_rcp_f32_e32 v4, v4
	ds_write2_b32 v8, v1, v2 offset0:64 offset1:96
	v_mul_f32_e32 v1, v43, v85
	v_mul_f32_e32 v2, v27, v85
	ds_write2_b32 v8, v1, v2 offset0:128 offset1:160
	v_mul_f32_e32 v1, v75, v85
	v_mul_f32_e32 v2, v59, v85
	v_rcp_f32_e32 v5, v5
	ds_write2_b32 v8, v1, v2 offset0:192 offset1:224
	v_mul_f32_e32 v1, v44, v0
	v_mul_f32_e32 v2, v28, v0
	v_add_u32_e32 v8, 0x3000, v7
	ds_write2_b32 v8, v1, v2 offset1:32
	v_mul_f32_e32 v1, v76, v0
	v_mul_f32_e32 v0, v60, v0
	v_rcp_f32_e32 v6, v6
	ds_write2_b32 v8, v1, v0 offset0:64 offset1:96
	v_mul_f32_e32 v0, v45, v4
	v_mul_f32_e32 v1, v29, v4
	ds_write2_b32 v8, v0, v1 offset0:128 offset1:160
	v_mul_f32_e32 v0, v77, v4
	v_mul_f32_e32 v1, v61, v4
	ds_write2_b32 v8, v0, v1 offset0:192 offset1:224
	v_mul_f32_e32 v0, v46, v5
	v_mul_f32_e32 v1, v30, v5
	v_add_u32_e32 v2, 0x3400, v7
	ds_write2_b32 v2, v0, v1 offset1:32
	v_mul_f32_e32 v0, v78, v5
	v_mul_f32_e32 v1, v62, v5
	ds_write2_b32 v2, v0, v1 offset0:64 offset1:96
	v_mul_f32_e32 v0, v47, v6
	v_mul_f32_e32 v1, v31, v6
	ds_write2_b32 v2, v0, v1 offset0:128 offset1:160
	v_mul_f32_e32 v0, v79, v6
	v_mul_f32_e32 v1, v63, v6
	ds_write2_b32 v2, v0, v1 offset0:192 offset1:224
	v_lshrrev_b32_e32 v4, 4, v145
	v_or_b32_e32 v0, s78, v4
	v_lshlrev_b32_e32 v2, 12, v0
	v_lshl_add_u64 v[0:1], s[0:1], 0, v[2:3]
	s_lshl_b32 s0, s38, 7
	s_waitcnt lgkmcnt(0)
	s_ashr_i32 s1, s0, 31
	v_lshl_add_u64 v[0:1], s[0:1], 1, v[0:1]
	v_and_b32_e32 v5, 15, v145
	v_lshlrev_b32_e32 v6, 4, v5
	v_mov_b32_e32 v7, v3
	v_lshl_add_u64 v[0:1], v[0:1], 0, v[6:7]
	v_lshlrev_b32_e32 v2, 9, v4
	v_lshl_add_u32 v2, v5, 5, v2
	v_add_u32_e32 v2, s2, v2
	ds_read_b128 v[8:11], v2
	ds_read_b128 v[12:15], v2 offset:16
	ds_read_b128 v[16:19], v2 offset:2048
	ds_read_b128 v[20:23], v2 offset:2064
	ds_read_b128 v[24:27], v2 offset:4096
	ds_read_b128 v[28:31], v2 offset:4112
	ds_read_b128 v[32:35], v2 offset:6144
	ds_read_b128 v[36:39], v2 offset:6160
	ds_read_b128 v[40:43], v2 offset:8192
	ds_read_b128 v[44:47], v2 offset:8208
	ds_read_b128 v[48:51], v2 offset:10240
	ds_read_b128 v[52:55], v2 offset:10256
	ds_read_b128 v[56:59], v2 offset:12288
	ds_read_b128 v[60:63], v2 offset:12304
	ds_read_b128 v[64:67], v2 offset:14336
	ds_read_b128 v[68:71], v2 offset:14352
	s_waitcnt lgkmcnt(14)
	v_cvt_pk_bf16_f32 v8, v8, v9
	v_cvt_pk_bf16_f32 v9, v10, v11
	v_cvt_pk_bf16_f32 v10, v12, v13
	v_cvt_pk_bf16_f32 v11, v14, v15
	global_store_dwordx4 v[0:1], v[8:11], off
	v_add_co_u32_e32 v0, vcc, 0x4000, v0
	s_nop 1
	v_addc_co_u32_e32 v1, vcc, 0, v1, vcc
	s_waitcnt lgkmcnt(12)
	v_cvt_pk_bf16_f32 v16, v16, v17
	v_cvt_pk_bf16_f32 v17, v18, v19
	v_cvt_pk_bf16_f32 v18, v20, v21
	v_cvt_pk_bf16_f32 v19, v22, v23
	global_store_dwordx4 v[0:1], v[16:19], off
	v_add_co_u32_e32 v0, vcc, 0x4000, v0
	s_nop 1
	v_addc_co_u32_e32 v1, vcc, 0, v1, vcc
	s_waitcnt lgkmcnt(10)
	v_cvt_pk_bf16_f32 v24, v24, v25
	v_cvt_pk_bf16_f32 v25, v26, v27
	v_cvt_pk_bf16_f32 v26, v28, v29
	v_cvt_pk_bf16_f32 v27, v30, v31
	global_store_dwordx4 v[0:1], v[24:27], off
	v_add_co_u32_e32 v0, vcc, 0x4000, v0
	s_nop 1
	v_addc_co_u32_e32 v1, vcc, 0, v1, vcc
	s_waitcnt lgkmcnt(8)
	v_cvt_pk_bf16_f32 v32, v32, v33
	v_cvt_pk_bf16_f32 v33, v34, v35
	v_cvt_pk_bf16_f32 v34, v36, v37
	v_cvt_pk_bf16_f32 v35, v38, v39
	global_store_dwordx4 v[0:1], v[32:35], off
	v_add_co_u32_e32 v0, vcc, 0x4000, v0
	s_nop 1
	v_addc_co_u32_e32 v1, vcc, 0, v1, vcc
	s_waitcnt lgkmcnt(6)
	v_cvt_pk_bf16_f32 v40, v40, v41
	v_cvt_pk_bf16_f32 v41, v42, v43
	v_cvt_pk_bf16_f32 v42, v44, v45
	v_cvt_pk_bf16_f32 v43, v46, v47
	global_store_dwordx4 v[0:1], v[40:43], off
	v_add_co_u32_e32 v0, vcc, 0x4000, v0
	s_nop 1
	v_addc_co_u32_e32 v1, vcc, 0, v1, vcc
	s_waitcnt lgkmcnt(4)
	v_cvt_pk_bf16_f32 v48, v48, v49
	v_cvt_pk_bf16_f32 v49, v50, v51
	v_cvt_pk_bf16_f32 v50, v52, v53
	v_cvt_pk_bf16_f32 v51, v54, v55
	global_store_dwordx4 v[0:1], v[48:51], off
	v_add_co_u32_e32 v0, vcc, 0x4000, v0
	s_nop 1
	v_addc_co_u32_e32 v1, vcc, 0, v1, vcc
	s_waitcnt lgkmcnt(2)
	v_cvt_pk_bf16_f32 v56, v56, v57
	v_cvt_pk_bf16_f32 v57, v58, v59
	v_cvt_pk_bf16_f32 v58, v60, v61
	v_cvt_pk_bf16_f32 v59, v62, v63
	global_store_dwordx4 v[0:1], v[56:59], off
	v_add_co_u32_e32 v0, vcc, 0x4000, v0
	s_nop 1
	v_addc_co_u32_e32 v1, vcc, 0, v1, vcc
	s_waitcnt lgkmcnt(0)
	v_cvt_pk_bf16_f32 v64, v64, v65
	v_cvt_pk_bf16_f32 v65, v66, v67
	v_cvt_pk_bf16_f32 v66, v68, v69
	v_cvt_pk_bf16_f32 v67, v70, v71
	global_store_dwordx4 v[0:1], v[64:67], off
	s_mov_b64 s[0:1], 0
